# P3 chunk tail: K' scaling moved before the output-gate part; gate part (VALU) and state update (MFMA/LDS) share one barrier-free region, waves 0-3 run gate first, waves 4-7 state update first (the two
# speedup vs baseline: 1.0066x; 1.0063x over previous
.LBB0_773:
	s_or_b64 exec, exec, s[0:1]
	s_add_i32 s0, 0, 0x21000
	s_waitcnt lgkmcnt(0)
	s_barrier
	v_lshl_add_u32 v121, v143, 2, s0
	ds_read_b128 v[234:237], v121
	s_waitcnt lgkmcnt(1)
	v_lshlrev_b32_e32 v134, 6, v196
	v_cmp_gt_i32_e64 s[6:7], s86, v132
	v_or_b32_e32 v188, 1, v182
	s_and_b64 s[8:9], s[2:3], s[6:7]
	s_waitcnt lgkmcnt(0)
	v_mul_f32_e32 v48, v48, v234
	v_bfe_u32 v121, v48, 16, 1
	v_mul_f32_e32 v49, v49, v235
	v_add3_u32 v48, v48, v121, s68
	ds_write_b16_d16_hi v222, v48
	v_bfe_u32 v48, v49, 16, 1
	v_add3_u32 v48, v49, v48, s68
	ds_write_b16_d16_hi v225, v48
	v_mul_f32_e32 v48, v50, v236
	v_bfe_u32 v49, v48, 16, 1
	v_add3_u32 v48, v48, v49, s68
	ds_write_b16_d16_hi v229, v48
	v_lshl_add_u32 v48, v113, 2, s0
	ds_read_b128 v[238:241], v48
	v_mul_f32_e32 v48, v51, v237
	v_bfe_u32 v49, v48, 16, 1
	v_add3_u32 v48, v48, v49, s68
	ds_write_b16_d16_hi v211, v48
	s_waitcnt lgkmcnt(1)
	v_mul_f32_e32 v48, v52, v238
	v_bfe_u32 v49, v48, 16, 1
	v_add3_u32 v48, v48, v49, s68
	ds_write_b16_d16_hi v207, v48
	v_mul_f32_e32 v48, v53, v239
	v_bfe_u32 v49, v48, 16, 1
	v_add3_u32 v48, v48, v49, s68
	ds_write_b16_d16_hi v210, v48
	v_mul_f32_e32 v48, v54, v240
	v_bfe_u32 v49, v48, 16, 1
	v_add3_u32 v48, v48, v49, s68
	ds_write_b16_d16_hi v214, v48
	v_lshl_add_u32 v48, v126, 2, s0
	ds_read_b128 v[48:51], v48
	v_mul_f32_e32 v52, v55, v241
	v_bfe_u32 v53, v52, 16, 1
	v_add3_u32 v52, v52, v53, s68
	ds_write_b16_d16_hi v213, v52
	s_waitcnt lgkmcnt(1)
	v_mul_f32_e32 v52, v56, v48
	v_bfe_u32 v53, v52, 16, 1
	v_add3_u32 v52, v52, v53, s68
	ds_write_b16_d16_hi v215, v52
	v_mul_f32_e32 v52, v57, v49
	v_bfe_u32 v53, v52, 16, 1
	v_add3_u32 v52, v52, v53, s68
	ds_write_b16_d16_hi v217, v52
	v_mul_f32_e32 v52, v58, v50
	v_bfe_u32 v53, v52, 16, 1
	v_add3_u32 v52, v52, v53, s68
	ds_write_b16_d16_hi v219, v52
	v_lshl_add_u32 v52, v123, 2, s0
	ds_read_b128 v[52:55], v52
	v_mul_f32_e32 v56, v59, v51
	v_bfe_u32 v57, v56, 16, 1
	v_add3_u32 v56, v56, v57, s68
	ds_write_b16_d16_hi v204, v56
	s_waitcnt lgkmcnt(1)
	v_mul_f32_e32 v56, v60, v52
	v_bfe_u32 v57, v56, 16, 1
	v_add3_u32 v56, v56, v57, s68
	ds_write_b16_d16_hi v202, v56
	v_mul_f32_e32 v56, v61, v53
	v_bfe_u32 v57, v56, 16, 1
	v_add3_u32 v56, v56, v57, s68
	ds_write_b16_d16_hi v203, v56
	v_mul_f32_e32 v56, v62, v54
	v_bfe_u32 v57, v56, 16, 1
	v_add3_u32 v56, v56, v57, s68
	ds_write_b16_d16_hi v205, v56
	v_mul_f32_e32 v56, v63, v55
	v_bfe_u32 v57, v56, 16, 1
	v_add3_u32 v56, v56, v57, s68
	v_mul_f32_e32 v32, v32, v234
	ds_write_b16_d16_hi v206, v56
	v_bfe_u32 v56, v32, 16, 1
	v_add3_u32 v32, v32, v56, s68
	ds_write_b16_d16_hi v208, v32
	v_mul_f32_e32 v32, v33, v235
	v_bfe_u32 v33, v32, 16, 1
	v_add3_u32 v32, v32, v33, s68
	ds_write_b16_d16_hi v209, v32
	v_mul_f32_e32 v32, v34, v236
	v_bfe_u32 v33, v32, 16, 1
	v_add3_u32 v32, v32, v33, s68
	ds_write_b16_d16_hi v212, v32
	v_mul_f32_e32 v32, v35, v237
	v_bfe_u32 v33, v32, 16, 1
	v_add3_u32 v32, v32, v33, s68
	ds_write_b16_d16_hi v216, v32
	v_mul_f32_e32 v32, v36, v238
	v_bfe_u32 v33, v32, 16, 1
	v_add3_u32 v32, v32, v33, s68
	ds_write_b16_d16_hi v218, v32
	v_mul_f32_e32 v32, v37, v239
	v_bfe_u32 v33, v32, 16, 1
	v_add3_u32 v32, v32, v33, s68
	ds_write_b16_d16_hi v220, v32
	v_mul_f32_e32 v32, v38, v240
	v_bfe_u32 v33, v32, 16, 1
	v_add3_u32 v32, v32, v33, s68
	ds_write_b16_d16_hi v221, v32
	v_mul_f32_e32 v32, v39, v241
	v_bfe_u32 v33, v32, 16, 1
	v_add3_u32 v32, v32, v33, s68
	ds_write_b16_d16_hi v223, v32
	v_mul_f32_e32 v32, v40, v48
	v_bfe_u32 v33, v32, 16, 1
	v_add3_u32 v32, v32, v33, s68
	ds_write_b16_d16_hi v224, v32
	v_mul_f32_e32 v32, v41, v49
	v_bfe_u32 v33, v32, 16, 1
	v_add3_u32 v32, v32, v33, s68
	ds_write_b16_d16_hi v226, v32
	v_mul_f32_e32 v32, v42, v50
	v_bfe_u32 v33, v32, 16, 1
	v_add3_u32 v32, v32, v33, s68
	ds_write_b16_d16_hi v227, v32
	v_mul_f32_e32 v32, v43, v51
	v_bfe_u32 v33, v32, 16, 1
	v_add3_u32 v32, v32, v33, s68
	ds_write_b16_d16_hi v228, v32
	v_mul_f32_e32 v32, v44, v52
	v_bfe_u32 v33, v32, 16, 1
	v_add3_u32 v32, v32, v33, s68
	ds_write_b16_d16_hi v230, v32
	v_mul_f32_e32 v32, v45, v53
	v_bfe_u32 v33, v32, 16, 1
	v_add3_u32 v32, v32, v33, s68
	ds_write_b16_d16_hi v231, v32
	v_mul_f32_e32 v32, v46, v54
	v_bfe_u32 v33, v32, 16, 1
	v_add3_u32 v32, v32, v33, s68
	ds_write_b16_d16_hi v232, v32
	v_mul_f32_e32 v32, v47, v55
	v_bfe_u32 v33, v32, 16, 1
	v_add3_u32 v32, v32, v33, s68
	v_ashrrev_i32_e32 v121, 31, v120
	ds_write_b16_d16_hi v233, v32
	v_lshl_add_u64 v[32:33], s[66:67], 0, v[120:121]
	v_lshlrev_b64 v[34:35], 13, v[32:33]
	v_lshl_add_u64 v[38:39], s[52:53], 0, v[34:35]
	s_waitcnt lgkmcnt(0)
	s_barrier
	ds_read_b128 v[42:45], v191 offset:32768
	v_add_u32_e32 v32, 0x20c00, v192
	ds_read_b32 v40, v32
	s_waitcnt lgkmcnt(1)
	v_and_b32_e32 v35, 0xffff0000, v43
	v_and_b32_e32 v34, 0xffff0000, v42
	v_and_b32_e32 v39, 0xffff0000, v45
	v_and_b32_e32 v38, 0xffff0000, v44
	v_lshlrev_b32_e32 v33, 16, v43
	v_lshlrev_b32_e32 v32, 16, v42
	s_waitcnt lgkmcnt(0)
	v_pk_mul_f32 v[34:35], v[40:41], v[34:35] op_sel_hi:[0,1]
	v_lshlrev_b32_e32 v37, 16, v45
	v_lshlrev_b32_e32 v36, 16, v44
	v_pk_mul_f32 v[38:39], v[40:41], v[38:39] op_sel_hi:[0,1]
	v_pk_mul_f32 v[32:33], v[40:41], v[32:33] op_sel_hi:[0,1]
	v_pk_mul_f32 v[36:37], v[40:41], v[36:37] op_sel_hi:[0,1]
	v_bfe_u32 v41, v39, 16, 1
	v_bfe_u32 v42, v38, 16, 1
	v_bfe_u32 v43, v35, 16, 1
	v_bfe_u32 v44, v34, 16, 1
	v_add3_u32 v44, v34, v44, s68
	v_add3_u32 v43, v35, v43, s68
	v_add3_u32 v34, v38, v42, s68
	v_add3_u32 v35, v39, v41, s68
	v_bfe_u32 v41, v36, 16, 1
	v_bfe_u32 v42, v37, 16, 1
	v_add3_u32 v37, v37, v42, s68
	v_add3_u32 v36, v36, v41, s68
	v_bfe_u32 v38, v32, 16, 1
	v_bfe_u32 v39, v33, 16, 1
	v_lshrrev_b32_e32 v41, 16, v36
	v_lshrrev_b32_e32 v36, 16, v37
	v_add3_u32 v33, v33, v39, s68
	v_add3_u32 v32, v32, v38, s68
	v_and_or_b32 v35, v35, s82, v36
	ds_read_b128 v[36:39], v190 offset:32768
	v_lshrrev_b32_e32 v32, 16, v32
	v_lshrrev_b32_e32 v33, 16, v33
	v_and_or_b32 v34, v34, s82, v41
	v_and_or_b32 v33, v43, s82, v33
	v_and_or_b32 v32, v44, s82, v32
	ds_write_b128 v191, v[32:35] offset:32768
	s_waitcnt lgkmcnt(1)
	v_lshlrev_b32_e32 v33, 16, v37
	v_lshlrev_b32_e32 v32, 16, v36
	v_and_b32_e32 v35, 0xffff0000, v37
	v_and_b32_e32 v34, 0xffff0000, v36
	v_lshlrev_b32_e32 v37, 16, v39
	v_lshlrev_b32_e32 v36, 16, v38
	v_and_b32_e32 v39, 0xffff0000, v39
	v_and_b32_e32 v38, 0xffff0000, v38
	v_pk_mul_f32 v[34:35], v[40:41], v[34:35] op_sel_hi:[0,1]
	v_pk_mul_f32 v[38:39], v[40:41], v[38:39] op_sel_hi:[0,1]
	v_pk_mul_f32 v[32:33], v[40:41], v[32:33] op_sel_hi:[0,1]
	v_pk_mul_f32 v[36:37], v[40:41], v[36:37] op_sel_hi:[0,1]
	v_bfe_u32 v41, v39, 16, 1
	v_bfe_u32 v42, v38, 16, 1
	v_bfe_u32 v43, v35, 16, 1
	v_bfe_u32 v44, v34, 16, 1
	v_add3_u32 v44, v34, v44, s68
	v_add3_u32 v43, v35, v43, s68
	v_add3_u32 v34, v38, v42, s68
	v_add3_u32 v35, v39, v41, s68
	v_bfe_u32 v41, v36, 16, 1
	v_bfe_u32 v42, v37, 16, 1
	v_add3_u32 v37, v37, v42, s68
	v_add3_u32 v36, v36, v41, s68
	v_bfe_u32 v38, v32, 16, 1
	v_bfe_u32 v39, v33, 16, 1
	v_lshrrev_b32_e32 v41, 16, v36
	v_lshrrev_b32_e32 v36, 16, v37
	v_add3_u32 v33, v33, v39, s68
	v_add3_u32 v32, v32, v38, s68
	v_and_or_b32 v35, v35, s82, v36
	ds_read_b128 v[36:39], v161 offset:32768
	v_lshrrev_b32_e32 v32, 16, v32
	v_lshrrev_b32_e32 v33, 16, v33
	v_and_or_b32 v34, v34, s82, v41
	v_and_or_b32 v33, v43, s82, v33
	v_and_or_b32 v32, v44, s82, v32
	ds_write_b128 v190, v[32:35] offset:32768
	s_waitcnt lgkmcnt(1)
	v_lshlrev_b32_e32 v33, 16, v37
	v_lshlrev_b32_e32 v32, 16, v36
	v_and_b32_e32 v35, 0xffff0000, v37
	v_and_b32_e32 v34, 0xffff0000, v36
	v_pk_mul_f32 v[36:37], v[40:41], v[32:33] op_sel_hi:[0,1]
	v_pk_mul_f32 v[32:33], v[40:41], v[34:35] op_sel_hi:[0,1]
	v_lshlrev_b32_e32 v35, 16, v39
	v_lshlrev_b32_e32 v34, 16, v38
	v_and_b32_e32 v39, 0xffff0000, v39
	v_and_b32_e32 v38, 0xffff0000, v38
	v_pk_mul_f32 v[42:43], v[40:41], v[34:35] op_sel_hi:[0,1]
	v_pk_mul_f32 v[34:35], v[40:41], v[38:39] op_sel_hi:[0,1]
	v_bfe_u32 v38, v35, 16, 1
	v_bfe_u32 v44, v32, 16, 1
	v_bfe_u32 v39, v34, 16, 1
	v_bfe_u32 v41, v33, 16, 1
	v_add3_u32 v32, v32, v44, s68
	v_add3_u32 v35, v35, v38, s68
	v_bfe_u32 v38, v36, 16, 1
	v_bfe_u32 v44, v43, 16, 1
	v_add3_u32 v33, v33, v41, s68
	v_add3_u32 v34, v34, v39, s68
	v_bfe_u32 v39, v37, 16, 1
	v_bfe_u32 v41, v42, 16, 1
	v_add3_u32 v44, v43, v44, s68
	v_add3_u32 v36, v36, v38, s68
	v_add3_u32 v43, v42, v41, s68
	v_add3_u32 v37, v37, v39, s68
	v_lshrrev_b32_e32 v41, 16, v36
	v_lshrrev_b32_e32 v36, 16, v44
	v_lshrrev_b32_e32 v42, 16, v37
	v_and_or_b32 v35, v35, s82, v36
	ds_read_b128 v[36:39], v117 offset:32768
	v_lshrrev_b32_e32 v43, 16, v43
	v_and_or_b32 v34, v34, s82, v43
	v_and_or_b32 v33, v33, s82, v42
	v_and_or_b32 v32, v32, s82, v41
	ds_write_b128 v161, v[32:35] offset:32768
	s_waitcnt lgkmcnt(1)
	v_lshlrev_b32_e32 v33, 16, v37
	v_lshlrev_b32_e32 v32, 16, v36
	v_and_b32_e32 v35, 0xffff0000, v37
	v_and_b32_e32 v34, 0xffff0000, v36
	v_lshlrev_b32_e32 v37, 16, v39
	v_lshlrev_b32_e32 v36, 16, v38
	v_and_b32_e32 v39, 0xffff0000, v39
	v_and_b32_e32 v38, 0xffff0000, v38
	v_pk_mul_f32 v[34:35], v[40:41], v[34:35] op_sel_hi:[0,1]
	v_pk_mul_f32 v[38:39], v[40:41], v[38:39] op_sel_hi:[0,1]
	v_pk_mul_f32 v[32:33], v[40:41], v[32:33] op_sel_hi:[0,1]
	v_pk_mul_f32 v[36:37], v[40:41], v[36:37] op_sel_hi:[0,1]
	v_bfe_u32 v40, v39, 16, 1
	v_bfe_u32 v41, v38, 16, 1
	v_bfe_u32 v42, v35, 16, 1
	v_bfe_u32 v43, v34, 16, 1
	v_add3_u32 v43, v34, v43, s68
	v_add3_u32 v42, v35, v42, s68
	v_add3_u32 v34, v38, v41, s68
	v_add3_u32 v35, v39, v40, s68
	v_bfe_u32 v38, v32, 16, 1
	v_bfe_u32 v39, v33, 16, 1
	v_bfe_u32 v40, v36, 16, 1
	v_bfe_u32 v41, v37, 16, 1
	v_add3_u32 v37, v37, v41, s68
	v_add3_u32 v36, v36, v40, s68
	v_add3_u32 v33, v33, v39, s68
	v_add3_u32 v32, v32, v38, s68
	v_lshrrev_b32_e32 v32, 16, v32
	v_lshrrev_b32_e32 v33, 16, v33
	v_lshrrev_b32_e32 v36, 16, v36
	v_lshrrev_b32_e32 v37, 16, v37
	v_and_or_b32 v35, v35, s82, v37
	v_and_or_b32 v34, v34, s82, v36
	v_and_or_b32 v33, v42, s82, v33
	v_and_or_b32 v32, v43, s82, v32
	ds_write_b128 v117, v[32:35] offset:32768
	s_and_saveexec_b64 s[0:1], s[8:9]
	s_cbranch_execz .LBB0_775
	v_lshl_add_u32 v32, v132, 2, 0
	v_add_u32_e32 v32, 0x20e00, v32
	ds_read_b32 v33, v32
	s_waitcnt lgkmcnt(0)
	v_mul_f32_e32 v33, v109, v33
	ds_write_b32 v32, v33
.LBB0_775:
	s_or_b64 exec, exec, s[0:1]
	s_waitcnt lgkmcnt(0)
	s_barrier
	v_readfirstlane_b32 s98, v128
	s_lshr_b32 s98, s98, 8
	s_mov_b32 s99, 0
.Lp3_tail_step:
	s_xor_b32 s100, s98, s99
	s_cmp_lg_u32 s100, 0
	s_cbranch_scc1 .Lp3_tail_state
	v_ashrrev_i32_e32 v121, 31, v120
	v_lshl_add_u64 v[32:33], s[66:67], 0, v[120:121]
	v_lshlrev_b64 v[34:35], 13, v[32:33]
	v_lshl_add_u64 v[38:39], s[52:53], 0, v[34:35]
	v_lshl_add_u64 v[34:35], v[38:39], 0, v[134:135]
	global_load_dwordx4 v[40:43], v[34:35], off offset:3072
	v_lshlrev_b32_e32 v121, 7, v196
	global_load_dwordx4 v[48:51], v121, s[18:19]
	ds_read_b128 v[44:47], v117
	ds_read_b128 v[52:55], v191
	ds_read_b128 v[56:59], v190
	ds_read_b128 v[60:63], v161
	global_load_dwordx4 v[200:203], v121, s[18:19] offset:16
	s_waitcnt lgkmcnt(3)
	v_and_b32_e32 v34, 0xffff0000, v46
	v_lshlrev_b32_e32 v35, 16, v46
	v_and_b32_e32 v36, 0xffff0000, v47
	v_lshlrev_b32_e32 v37, 16, v47
	s_waitcnt lgkmcnt(2)
	v_lshlrev_b32_e32 v209, 16, v53
	v_lshlrev_b32_e32 v208, 16, v52
	v_and_b32_e32 v53, 0xffff0000, v53
	v_and_b32_e32 v52, 0xffff0000, v52
	v_pk_mul_f32 v[210:211], v[208:209], v[208:209]
	v_pk_mul_f32 v[212:213], v[52:53], v[52:53]
	v_lshlrev_b32_e32 v221, 16, v55
	v_lshlrev_b32_e32 v220, 16, v54
	v_and_b32_e32 v55, 0xffff0000, v55
	v_and_b32_e32 v54, 0xffff0000, v54
	v_pk_mul_f32 v[222:223], v[220:221], v[220:221]
	v_pk_mul_f32 v[224:225], v[54:55], v[54:55]
	s_waitcnt lgkmcnt(1)
	v_lshlrev_b32_e32 v235, 16, v57
	v_lshlrev_b32_e32 v234, 16, v56
	v_and_b32_e32 v237, 0xffff0000, v57
	v_and_b32_e32 v236, 0xffff0000, v56
	v_pk_mul_f32 v[56:57], v[234:235], v[234:235]
	v_pk_mul_f32 v[238:239], v[236:237], v[236:237]
	v_lshlrev_b32_e32 v241, 16, v59
	v_lshlrev_b32_e32 v240, 16, v58
	v_and_b32_e32 v243, 0xffff0000, v59
	v_and_b32_e32 v242, 0xffff0000, v58
	v_pk_mul_f32 v[58:59], v[240:241], v[240:241]
	v_pk_mul_f32 v[244:245], v[242:243], v[242:243]
	s_waitcnt lgkmcnt(0)
	v_lshlrev_b32_e32 v247, 16, v61
	v_lshlrev_b32_e32 v246, 16, v60
	v_and_b32_e32 v249, 0xffff0000, v61
	v_and_b32_e32 v248, 0xffff0000, v60
	v_pk_mul_f32 v[60:61], v[246:247], v[246:247]
	v_pk_mul_f32 v[250:251], v[248:249], v[248:249]
	v_pk_mul_f32 v[204:205], v[34:35], v[34:35]
	v_pk_mul_f32 v[206:207], v[36:37], v[36:37]
	v_lshlrev_b64 v[32:33], 11, v[32:33]
	v_lshl_add_u64 v[32:33], s[54:55], 0, v[32:33]
	s_waitcnt vmcnt(2)
	v_lshlrev_b32_e32 v46, 16, v40
	v_mul_f32_e32 v47, 0xbfb8aa3b, v46
	v_exp_f32_e32 v136, v47
	v_lshlrev_b32_e32 v47, 16, v41
	v_and_b32_e32 v41, 0xffff0000, v41
	v_and_b32_e32 v40, 0xffff0000, v40
	v_mul_f32_e32 v137, 0xbfb8aa3b, v40
	v_mul_f32_e32 v121, 0xbfb8aa3b, v41
	v_exp_f32_e32 v137, v137
	v_exp_f32_e32 v121, v121
	v_mul_f32_e32 v189, 0xbfb8aa3b, v47
	v_exp_f32_e32 v189, v189
	v_add_f32_e32 v136, 1.0, v136
	v_rcp_f32_e32 v214, v136
	v_add_f32_e32 v136, 1.0, v137
	s_waitcnt vmcnt(1)
	v_mov_b32_e32 v218, v48
	v_add_f32_e32 v48, 1.0, v121
	v_rcp_f32_e32 v216, v136
	v_rcp_f32_e32 v217, v48
	v_add_f32_e32 v121, v210, v212
	v_add_f32_e32 v136, 1.0, v189
	v_add_f32_e32 v121, v211, v121
	v_rcp_f32_e32 v215, v136
	v_add_f32_e32 v121, v213, v121
	v_add_f32_e32 v121, v222, v121
	v_pk_mul_f32 v[40:41], v[216:217], v[40:41]
	v_add_f32_e32 v121, v224, v121
	v_cndmask_b32_e64 v216, v40, v216, s[2:3]
	v_lshlrev_b32_e32 v40, 16, v42
	v_add_f32_e32 v121, v223, v121
	v_pk_mul_f32 v[46:47], v[214:215], v[46:47]
	v_cndmask_b32_e64 v217, v41, v217, s[2:3]
	v_mul_f32_e32 v41, 0xbfb8aa3b, v40
	v_add_f32_e32 v121, v225, v121
	v_cndmask_b32_e64 v214, v46, v214, s[2:3]
	v_exp_f32_e32 v46, v41
	v_lshlrev_b32_e32 v41, 16, v43
	v_add_f32_e32 v56, v56, v121
	v_and_b32_e32 v227, 0xffff0000, v43
	v_mul_f32_e32 v43, 0xbfb8aa3b, v41
	v_add_f32_e32 v56, v238, v56
	v_exp_f32_e32 v43, v43
	v_add_f32_e32 v56, v57, v56
	v_add_f32_e32 v56, v239, v56
	v_add_f32_e32 v56, v58, v56
	v_add_f32_e32 v56, v244, v56
	v_add_f32_e32 v43, 1.0, v43
	v_add_f32_e32 v56, v59, v56
	v_and_b32_e32 v226, 0xffff0000, v42
	v_add_f32_e32 v42, 1.0, v46
	v_rcp_f32_e32 v229, v43
	v_mul_f32_e32 v43, 0xbfb8aa3b, v227
	v_add_f32_e32 v56, v245, v56
	v_rcp_f32_e32 v228, v42
	v_exp_f32_e32 v43, v43
	v_add_f32_e32 v56, v60, v56
	v_add_f32_e32 v56, v250, v56
	v_mov_b32_e32 v219, v50
	v_mov_b32_e32 v50, v49
	v_mul_f32_e32 v42, 0xbfb8aa3b, v226
	v_lshlrev_b32_e32 v49, 16, v63
	v_lshlrev_b32_e32 v48, 16, v62
	v_add_f32_e32 v56, v61, v56
	v_cndmask_b32_e64 v215, v47, v215, s[2:3]
	v_exp_f32_e32 v42, v42
	v_and_b32_e32 v47, 0xffff0000, v63
	v_and_b32_e32 v46, 0xffff0000, v62
	v_pk_mul_f32 v[62:63], v[48:49], v[48:49]
	v_add_f32_e32 v56, v251, v56
	v_pk_mul_f32 v[232:233], v[228:229], v[40:41]
	v_add_f32_e32 v40, 1.0, v43
	v_pk_mul_f32 v[252:253], v[46:47], v[46:47]
	v_add_f32_e32 v56, v62, v56
	v_rcp_f32_e32 v231, v40
	v_lshlrev_b32_e32 v136, 16, v44
	v_and_b32_e32 v40, 0xffff0000, v44
	v_add_f32_e32 v56, v252, v56
	v_lshlrev_b32_e32 v137, 16, v45
	v_and_b32_e32 v41, 0xffff0000, v45
	v_mov_b32_e32 v44, v40
	v_mov_b32_e32 v45, v136
	v_add_f32_e32 v56, v63, v56
	v_add_f32_e32 v42, 1.0, v42
	v_pk_mul_f32 v[44:45], v[44:45], v[44:45]
	v_add_f32_e32 v56, v253, v56
	v_rcp_f32_e32 v230, v42
	v_mov_b32_e32 v42, v41
	v_mov_b32_e32 v43, v137
	v_add_f32_e32 v45, v45, v56
	v_pk_mul_f32 v[42:43], v[42:43], v[42:43]
	v_add_f32_e32 v44, v44, v45
	v_add_f32_e32 v43, v43, v44
	v_add_f32_e32 v42, v42, v43
	v_add_f32_e32 v42, v205, v42
	v_add_f32_e32 v42, v204, v42
	v_add_f32_e32 v42, v207, v42
	v_add_f32_e32 v56, v206, v42
	ds_bpermute_b32 v58, v197, v56
	v_pk_mul_f32 v[44:45], v[230:231], v[226:227]
	s_waitcnt vmcnt(0)
	v_lshlrev_b32_e32 v238, 4, v194
	v_mov_b32_e32 v239, 0
	v_lshl_add_u64 v[244:245], v[38:39], 0, v[238:239]
	global_load_dwordx4 v[210:213], v[244:245], off offset:3072
	v_lshlrev_b32_e32 v238, 5, v194
	global_load_dwordx4 v[222:225], v238, s[18:19]
	global_load_dwordx4 v[250:253], v238, s[18:19] offset:16
	v_mov_b32_e32 v59, v202
	v_cndmask_b32_e64 v57, v45, v231, s[2:3]
	v_cndmask_b32_e64 v43, v233, v229, s[2:3]
	s_waitcnt lgkmcnt(0)
	v_add_f32_e32 v45, v56, v58
	ds_bpermute_b32 v60, v198, v45
	v_cndmask_b32_e64 v56, v44, v230, s[2:3]
	v_mov_b32_e32 v58, v200
	v_cndmask_b32_e64 v42, v232, v228, s[2:3]
	v_mov_b32_e32 v202, v201
	s_waitcnt lgkmcnt(0)
	v_add_f32_e32 v44, v45, v60
	v_fmamk_f32 v44, v44, 0x3c000000, v133
	v_cmp_gt_f32_e32 vcc, s85, v44
	v_mul_f32_e32 v45, 0x4b800000, v44
	v_lshl_add_u64 v[60:61], v[32:33], 0, v[134:135]
	v_cndmask_b32_e32 v44, v44, v45, vcc
	v_rsq_f32_e32 v44, v44
	v_lshlrev_b32_e32 v134, 4, v195
	v_lshl_add_u64 v[62:63], v[38:39], 0, v[134:135]
	v_mul_f32_e32 v45, 0x45800000, v44
	v_cndmask_b32_e32 v44, v44, v45, vcc
	v_pk_mul_f32 v[52:53], v[44:45], v[52:53] op_sel_hi:[0,1]
	v_pk_mul_f32 v[50:51], v[50:51], v[52:53]
	v_pk_mul_f32 v[52:53], v[44:45], v[220:221] op_sel_hi:[0,1]
	v_pk_mul_f32 v[52:53], v[58:59], v[52:53]
	v_pk_mul_f32 v[196:197], v[44:45], v[208:209] op_sel_hi:[0,1]
	v_pk_mul_f32 v[42:43], v[42:43], v[52:53]
	v_pk_mul_f32 v[52:53], v[44:45], v[54:55] op_sel_hi:[0,1]
	v_pk_mul_f32 v[52:53], v[202:203], v[52:53]
	v_pk_mul_f32 v[196:197], v[218:219], v[196:197]
	v_pk_mul_f32 v[50:51], v[216:217], v[50:51]
	v_pk_mul_f32 v[52:53], v[56:57], v[52:53]
	v_pk_mul_f32 v[196:197], v[214:215], v[196:197]
	v_bfe_u32 v45, v53, 16, 1
	v_bfe_u32 v54, v52, 16, 1
	v_bfe_u32 v55, v51, 16, 1
	v_bfe_u32 v56, v50, 16, 1
	v_add3_u32 v50, v50, v56, s68
	v_add3_u32 v51, v51, v55, s68
	v_add3_u32 v52, v52, v54, s68
	v_add3_u32 v45, v53, v45, s68
	v_bfe_u32 v53, v196, 16, 1
	v_bfe_u32 v54, v197, 16, 1
	v_bfe_u32 v55, v42, 16, 1
	v_bfe_u32 v56, v43, 16, 1
	v_add3_u32 v43, v43, v56, s68
	v_add3_u32 v42, v42, v55, s68
	v_add3_u32 v54, v197, v54, s68
	v_add3_u32 v53, v196, v53, s68
	v_lshrrev_b32_e32 v55, 16, v53
	v_lshrrev_b32_e32 v54, 16, v54
	v_lshrrev_b32_e32 v42, 16, v42
	v_lshrrev_b32_e32 v43, 16, v43
	v_and_or_b32 v53, v45, s82, v43
	v_and_or_b32 v52, v52, s82, v42
	v_and_or_b32 v51, v51, s82, v54
	v_and_or_b32 v50, v50, s82, v55
	v_and_b32_e32 v60, 0xffffffc0, v191
	ds_write_b128 v60, v[50:53]
	global_load_dwordx4 v[50:53], v[62:63], off offset:3072
	v_lshlrev_b32_e32 v42, 5, v195
	global_load_dwordx4 v[54:57], v42, s[18:19]
	global_load_dwordx4 v[58:61], v42, s[18:19] offset:16
	v_lshl_add_u64 v[42:43], v[32:33], 0, v[134:135]
	v_lshlrev_b32_e32 v134, 4, v194
	v_lshl_add_u64 v[62:63], v[38:39], 0, v[134:135]
	s_waitcnt vmcnt(2)
	v_lshlrev_b32_e32 v196, 16, v50
	v_and_b32_e32 v50, 0xffff0000, v50
	v_mul_f32_e32 v45, 0xbfb8aa3b, v196
	v_lshlrev_b32_e32 v197, 16, v51
	v_exp_f32_e32 v45, v45
	v_mul_f32_e32 v121, 0xbfb8aa3b, v50
	v_exp_f32_e32 v121, v121
	v_mul_f32_e32 v189, 0xbfb8aa3b, v197
	v_exp_f32_e32 v189, v189
	v_add_f32_e32 v45, 1.0, v45
	v_rcp_f32_e32 v200, v45
	v_add_f32_e32 v45, 1.0, v121
	v_and_b32_e32 v51, 0xffff0000, v51
	v_rcp_f32_e32 v202, v45
	v_add_f32_e32 v45, 1.0, v189
	v_rcp_f32_e32 v201, v45
	v_pk_mul_f32 v[204:205], v[44:45], v[234:235] op_sel_hi:[0,1]
	v_mul_f32_e32 v45, 0xbfb8aa3b, v51
	v_exp_f32_e32 v45, v45
	v_pk_mul_f32 v[196:197], v[200:201], v[196:197]
	v_lshlrev_b32_e32 v198, 16, v52
	s_waitcnt vmcnt(1)
	v_mov_b32_e32 v207, v56
	v_add_f32_e32 v45, 1.0, v45
	v_rcp_f32_e32 v203, v45
	v_cndmask_b32_e64 v197, v197, v201, s[2:3]
	v_cndmask_b32_e64 v196, v196, v200, s[2:3]
	v_pk_mul_f32 v[200:201], v[44:45], v[236:237] op_sel_hi:[0,1]
	v_mov_b32_e32 v56, v55
	v_pk_mul_f32 v[50:51], v[202:203], v[50:51]
	v_and_b32_e32 v52, 0xffff0000, v52
	v_mov_b32_e32 v206, v54
	v_pk_mul_f32 v[54:55], v[56:57], v[200:201]
	v_mul_f32_e32 v45, 0xbfb8aa3b, v198
	v_cndmask_b32_e64 v51, v51, v203, s[2:3]
	v_cndmask_b32_e64 v50, v50, v202, s[2:3]
	v_lshlrev_b32_e32 v199, 16, v53
	v_exp_f32_e32 v45, v45
	v_pk_mul_f32 v[50:51], v[50:51], v[54:55]
	v_mul_f32_e32 v54, 0xbfb8aa3b, v52
	v_exp_f32_e32 v55, v54
	v_mul_f32_e32 v54, 0xbfb8aa3b, v199
	v_exp_f32_e32 v57, v54
	v_add_f32_e32 v45, 1.0, v45
	v_rcp_f32_e32 v54, v45
	v_add_f32_e32 v45, 1.0, v55
	v_and_b32_e32 v53, 0xffff0000, v53
	v_rcp_f32_e32 v56, v45
	v_add_f32_e32 v45, 1.0, v57
	v_rcp_f32_e32 v55, v45
	v_pk_mul_f32 v[200:201], v[44:45], v[240:241] op_sel_hi:[0,1]
	v_mul_f32_e32 v45, 0xbfb8aa3b, v53
	v_exp_f32_e32 v45, v45
	v_pk_mul_f32 v[198:199], v[54:55], v[198:199]
	s_waitcnt vmcnt(0)
	v_lshlrev_b32_e32 v230, 4, v193
	v_mov_b32_e32 v231, 0
	v_lshl_add_u64 v[232:233], v[38:39], 0, v[230:231]
	global_load_dwordx4 v[214:217], v[232:233], off offset:3072
	v_lshlrev_b32_e32 v230, 5, v193
	global_load_dwordx4 v[218:221], v230, s[18:19]
	global_load_dwordx4 v[226:229], v230, s[18:19] offset:16
	v_mov_b32_e32 v203, v60
	v_cndmask_b32_e64 v55, v199, v55, s[2:3]
	v_add_f32_e32 v45, 1.0, v45
	v_rcp_f32_e32 v57, v45
	v_cndmask_b32_e64 v54, v198, v54, s[2:3]
	v_pk_mul_f32 v[198:199], v[44:45], v[242:243] op_sel_hi:[0,1]
	v_mov_b32_e32 v60, v59
	v_pk_mul_f32 v[52:53], v[56:57], v[52:53]
	v_mov_b32_e32 v202, v58
	v_pk_mul_f32 v[58:59], v[60:61], v[198:199]
	v_cndmask_b32_e64 v53, v53, v57, s[2:3]
	v_cndmask_b32_e64 v52, v52, v56, s[2:3]
	v_pk_mul_f32 v[204:205], v[206:207], v[204:205]
	v_pk_mul_f32 v[200:201], v[202:203], v[200:201]
	v_pk_mul_f32 v[52:53], v[52:53], v[58:59]
	v_pk_mul_f32 v[196:197], v[196:197], v[204:205]
	v_pk_mul_f32 v[54:55], v[54:55], v[200:201]
	v_bfe_u32 v45, v53, 16, 1
	v_bfe_u32 v56, v52, 16, 1
	v_bfe_u32 v57, v51, 16, 1
	v_bfe_u32 v58, v50, 16, 1
	v_add3_u32 v50, v50, v58, s68
	v_add3_u32 v51, v51, v57, s68
	v_add3_u32 v52, v52, v56, s68
	v_add3_u32 v45, v53, v45, s68
	v_bfe_u32 v53, v196, 16, 1
	v_bfe_u32 v56, v197, 16, 1
	v_bfe_u32 v57, v54, 16, 1
	v_bfe_u32 v58, v55, 16, 1
	v_add3_u32 v55, v55, v58, s68
	v_add3_u32 v54, v54, v57, s68
	v_add3_u32 v56, v197, v56, s68
	v_add3_u32 v53, v196, v53, s68
	v_lshrrev_b32_e32 v57, 16, v53
	v_lshrrev_b32_e32 v56, 16, v56
	v_lshrrev_b32_e32 v54, 16, v54
	v_lshrrev_b32_e32 v53, 16, v55
	v_and_or_b32 v53, v45, s82, v53
	v_and_or_b32 v52, v52, s82, v54
	v_and_or_b32 v51, v51, s82, v56
	v_and_or_b32 v50, v50, s82, v57
	v_and_b32_e32 v42, 0xffffffc0, v191
	ds_write_b128 v42, v[50:53] offset:16
	v_mov_b32_e32 v50, v210
	v_mov_b32_e32 v51, v211
	v_mov_b32_e32 v52, v212
	v_mov_b32_e32 v53, v213
	v_mov_b32_e32 v54, v222
	v_mov_b32_e32 v55, v223
	v_mov_b32_e32 v56, v224
	v_mov_b32_e32 v57, v225
	v_mov_b32_e32 v58, v250
	v_mov_b32_e32 v59, v251
	v_mov_b32_e32 v60, v252
	v_mov_b32_e32 v61, v253
	v_lshlrev_b32_e32 v42, 5, v194
	v_lshl_add_u64 v[42:43], v[32:33], 0, v[134:135]
	v_lshlrev_b32_e32 v134, 4, v193
	v_lshl_add_u64 v[38:39], v[38:39], 0, v[134:135]
	v_lshl_add_u64 v[32:33], v[32:33], 0, v[134:135]
	v_lshlrev_b32_e32 v62, 16, v50
	v_and_b32_e32 v50, 0xffff0000, v50
	v_mul_f32_e32 v45, 0xbfb8aa3b, v62
	v_lshlrev_b32_e32 v63, 16, v51
	v_exp_f32_e32 v45, v45
	v_mul_f32_e32 v121, 0xbfb8aa3b, v50
	v_exp_f32_e32 v121, v121
	v_mul_f32_e32 v189, 0xbfb8aa3b, v63
	v_exp_f32_e32 v189, v189
	v_add_f32_e32 v45, 1.0, v45
	v_rcp_f32_e32 v196, v45
	v_add_f32_e32 v45, 1.0, v121
	v_and_b32_e32 v51, 0xffff0000, v51
	v_rcp_f32_e32 v198, v45
	v_add_f32_e32 v45, 1.0, v189
	v_rcp_f32_e32 v197, v45
	v_pk_mul_f32 v[200:201], v[44:45], v[246:247] op_sel_hi:[0,1]
	v_mul_f32_e32 v45, 0xbfb8aa3b, v51
	v_exp_f32_e32 v45, v45
	v_pk_mul_f32 v[62:63], v[196:197], v[62:63]
	v_lshlrev_b32_e32 v194, 16, v52
	v_mov_b32_e32 v203, v56
	v_add_f32_e32 v45, 1.0, v45
	v_rcp_f32_e32 v199, v45
	v_cndmask_b32_e64 v63, v63, v197, s[2:3]
	v_cndmask_b32_e64 v62, v62, v196, s[2:3]
	v_pk_mul_f32 v[196:197], v[44:45], v[248:249] op_sel_hi:[0,1]
	v_mov_b32_e32 v56, v55
	v_pk_mul_f32 v[50:51], v[198:199], v[50:51]
	v_and_b32_e32 v52, 0xffff0000, v52
	v_mov_b32_e32 v202, v54
	v_pk_mul_f32 v[54:55], v[56:57], v[196:197]
	v_mul_f32_e32 v45, 0xbfb8aa3b, v194
	v_cndmask_b32_e64 v51, v51, v199, s[2:3]
	v_cndmask_b32_e64 v50, v50, v198, s[2:3]
	v_lshlrev_b32_e32 v195, 16, v53
	v_exp_f32_e32 v45, v45
	v_pk_mul_f32 v[50:51], v[50:51], v[54:55]
	v_mul_f32_e32 v54, 0xbfb8aa3b, v52
	v_exp_f32_e32 v55, v54
	v_mul_f32_e32 v54, 0xbfb8aa3b, v195
	v_exp_f32_e32 v57, v54
	v_add_f32_e32 v45, 1.0, v45
	v_rcp_f32_e32 v54, v45
	v_add_f32_e32 v45, 1.0, v55
	v_and_b32_e32 v53, 0xffff0000, v53
	v_rcp_f32_e32 v56, v45
	v_add_f32_e32 v45, 1.0, v57
	v_rcp_f32_e32 v55, v45
	v_pk_mul_f32 v[48:49], v[44:45], v[48:49] op_sel_hi:[0,1]
	v_mul_f32_e32 v45, 0xbfb8aa3b, v53
	v_exp_f32_e32 v45, v45
	v_mov_b32_e32 v197, v60
	v_mov_b32_e32 v60, v59
	v_mov_b32_e32 v196, v58
	v_add_f32_e32 v45, 1.0, v45
	v_rcp_f32_e32 v57, v45
	v_pk_mul_f32 v[46:47], v[44:45], v[46:47] op_sel_hi:[0,1]
	v_pk_mul_f32 v[194:195], v[54:55], v[194:195]
	v_pk_mul_f32 v[46:47], v[60:61], v[46:47]
	v_pk_mul_f32 v[52:53], v[56:57], v[52:53]
	v_pk_mul_f32 v[200:201], v[202:203], v[200:201]
	v_cndmask_b32_e64 v53, v53, v57, s[2:3]
	v_cndmask_b32_e64 v52, v52, v56, s[2:3]
	v_pk_mul_f32 v[48:49], v[196:197], v[48:49]
	v_cndmask_b32_e64 v55, v195, v55, s[2:3]
	v_cndmask_b32_e64 v54, v194, v54, s[2:3]
	v_pk_mul_f32 v[46:47], v[52:53], v[46:47]
	v_pk_mul_f32 v[62:63], v[62:63], v[200:201]
	v_pk_mul_f32 v[48:49], v[54:55], v[48:49]
	v_bfe_u32 v45, v47, 16, 1
	v_bfe_u32 v52, v46, 16, 1
	v_bfe_u32 v53, v51, 16, 1
	v_bfe_u32 v54, v50, 16, 1
	v_add3_u32 v50, v50, v54, s68
	v_add3_u32 v51, v51, v53, s68
	v_add3_u32 v46, v46, v52, s68
	v_add3_u32 v45, v47, v45, s68
	v_bfe_u32 v47, v62, 16, 1
	v_bfe_u32 v52, v63, 16, 1
	v_bfe_u32 v53, v48, 16, 1
	v_bfe_u32 v54, v49, 16, 1
	v_add3_u32 v49, v49, v54, s68
	v_add3_u32 v48, v48, v53, s68
	v_add3_u32 v52, v63, v52, s68
	v_add3_u32 v47, v62, v47, s68
	v_lshrrev_b32_e32 v53, 16, v47
	v_lshrrev_b32_e32 v47, 16, v52
	v_lshrrev_b32_e32 v48, 16, v48
	v_lshrrev_b32_e32 v49, 16, v49
	v_and_or_b32 v49, v45, s82, v49
	v_and_or_b32 v48, v46, s82, v48
	v_and_or_b32 v47, v51, s82, v47
	v_and_or_b32 v46, v50, s82, v53
	v_and_b32_e32 v42, 0xffffffc0, v191
	ds_write_b128 v42, v[46:49] offset:32
	s_waitcnt vmcnt(0)
	v_mov_b32_e32 v46, v214
	v_mov_b32_e32 v47, v215
	v_mov_b32_e32 v48, v216
	v_mov_b32_e32 v49, v217
	v_mov_b32_e32 v50, v218
	v_mov_b32_e32 v51, v219
	v_mov_b32_e32 v52, v220
	v_mov_b32_e32 v53, v221
	v_mov_b32_e32 v54, v226
	v_mov_b32_e32 v55, v227
	v_mov_b32_e32 v56, v228
	v_mov_b32_e32 v57, v229
	v_lshlrev_b32_e32 v38, 5, v193
	s_waitcnt vmcnt(2)
	v_lshlrev_b32_e32 v38, 16, v46
	v_mul_f32_e32 v39, 0xbfb8aa3b, v38
	v_and_b32_e32 v42, 0xffff0000, v46
	v_exp_f32_e32 v45, v39
	v_lshlrev_b32_e32 v39, 16, v47
	v_mul_f32_e32 v46, 0xbfb8aa3b, v42
	v_and_b32_e32 v43, 0xffff0000, v47
	v_exp_f32_e32 v47, v46
	v_mul_f32_e32 v46, 0xbfb8aa3b, v39
	v_exp_f32_e32 v59, v46
	v_add_f32_e32 v45, 1.0, v45
	v_rcp_f32_e32 v46, v45
	v_add_f32_e32 v45, 1.0, v47
	v_rcp_f32_e32 v58, v45
	v_add_f32_e32 v45, 1.0, v59
	v_rcp_f32_e32 v47, v45
	v_pk_mul_f32 v[60:61], v[44:45], v[136:137] op_sel_hi:[0,1]
	v_mul_f32_e32 v45, 0xbfb8aa3b, v43
	v_exp_f32_e32 v45, v45
	s_waitcnt vmcnt(1)
	v_mov_b32_e32 v63, v52
	v_mov_b32_e32 v52, v51
	v_pk_mul_f32 v[38:39], v[46:47], v[38:39]
	v_add_f32_e32 v45, 1.0, v45
	v_rcp_f32_e32 v59, v45
	v_pk_mul_f32 v[40:41], v[44:45], v[40:41] op_sel_hi:[0,1]
	v_pk_mul_f32 v[40:41], v[52:53], v[40:41]
	v_cndmask_b32_e64 v39, v39, v47, s[2:3]
	v_pk_mul_f32 v[42:43], v[58:59], v[42:43]
	v_cndmask_b32_e64 v38, v38, v46, s[2:3]
	v_cndmask_b32_e64 v43, v43, v59, s[2:3]
	v_cndmask_b32_e64 v42, v42, v58, s[2:3]
	v_pk_mul_f32 v[40:41], v[42:43], v[40:41]
	v_lshlrev_b32_e32 v42, 16, v48
	v_mul_f32_e32 v43, 0xbfb8aa3b, v42
	v_and_b32_e32 v47, 0xffff0000, v49
	v_and_b32_e32 v46, 0xffff0000, v48
	v_exp_f32_e32 v45, v43
	v_lshlrev_b32_e32 v43, 16, v49
	v_mul_f32_e32 v48, 0xbfb8aa3b, v46
	v_mov_b32_e32 v52, v35
	v_mul_f32_e32 v35, 0xbfb8aa3b, v47
	v_exp_f32_e32 v49, v48
	v_mul_f32_e32 v48, 0xbfb8aa3b, v43
	v_exp_f32_e32 v35, v35
	v_exp_f32_e32 v51, v48
	v_add_f32_e32 v45, 1.0, v45
	v_rcp_f32_e32 v48, v45
	v_add_f32_e32 v45, 1.0, v49
	v_add_f32_e32 v35, 1.0, v35
	v_mov_b32_e32 v62, v50
	v_rcp_f32_e32 v50, v45
	v_add_f32_e32 v45, 1.0, v51
	v_rcp_f32_e32 v51, v35
	v_rcp_f32_e32 v49, v45
	v_mov_b32_e32 v35, v36
	v_mov_b32_e32 v53, v37
	s_waitcnt vmcnt(0)
	v_mov_b32_e32 v59, v56
	v_pk_mul_f32 v[34:35], v[44:45], v[34:35] op_sel_hi:[0,1]
	v_mov_b32_e32 v56, v55
	v_pk_mul_f32 v[36:37], v[50:51], v[46:47]
	v_pk_mul_f32 v[52:53], v[44:45], v[52:53] op_sel_hi:[0,1]
	v_mov_b32_e32 v58, v54
	v_pk_mul_f32 v[42:43], v[48:49], v[42:43]
	v_pk_mul_f32 v[34:35], v[56:57], v[34:35]
	v_cndmask_b32_e64 v37, v37, v51, s[2:3]
	v_cndmask_b32_e64 v36, v36, v50, s[2:3]
	v_pk_mul_f32 v[60:61], v[62:63], v[60:61]
	v_pk_mul_f32 v[52:53], v[58:59], v[52:53]
	v_cndmask_b32_e64 v43, v43, v49, s[2:3]
	v_cndmask_b32_e64 v42, v42, v48, s[2:3]
	v_pk_mul_f32 v[34:35], v[36:37], v[34:35]
	v_pk_mul_f32 v[38:39], v[38:39], v[60:61]
	v_pk_mul_f32 v[42:43], v[42:43], v[52:53]
	v_bfe_u32 v36, v35, 16, 1
	v_bfe_u32 v37, v34, 16, 1
	v_bfe_u32 v44, v41, 16, 1
	v_bfe_u32 v45, v40, 16, 1
	v_add3_u32 v40, v40, v45, s68
	v_add3_u32 v41, v41, v44, s68
	v_add3_u32 v34, v34, v37, s68
	v_add3_u32 v35, v35, v36, s68
	v_bfe_u32 v36, v38, 16, 1
	v_bfe_u32 v37, v39, 16, 1
	v_bfe_u32 v44, v42, 16, 1
	v_bfe_u32 v45, v43, 16, 1
	v_add3_u32 v43, v43, v45, s68
	v_add3_u32 v42, v42, v44, s68
	v_add3_u32 v37, v39, v37, s68
	v_add3_u32 v36, v38, v36, s68
	v_lshrrev_b32_e32 v38, 16, v36
	v_lshrrev_b32_e32 v39, 16, v37
	v_lshrrev_b32_e32 v36, 16, v42
	v_lshrrev_b32_e32 v37, 16, v43
	v_and_or_b32 v37, v35, s82, v37
	v_and_or_b32 v36, v34, s82, v36
	v_and_or_b32 v35, v41, s82, v39
	v_and_or_b32 v34, v40, s82, v38
	global_store_dwordx4 v[32:33], v[34:37], off
	v_and_b32_e32 v46, 0xffffffc0, v191
	ds_read_b128 v[50:53], v46
	ds_read_b128 v[54:57], v46 offset:16
	ds_read_b128 v[58:61], v46 offset:32
	s_waitcnt lgkmcnt(0)
	global_store_dwordx4 v[32:33], v[50:53], off offset:-48
	global_store_dwordx4 v[32:33], v[54:57], off offset:-32
	global_store_dwordx4 v[32:33], v[58:61], off offset:-16
	s_branch .Lp3_tail_next
.Lp3_tail_state:
	v_or_b32_e32 v32, s73, v174
	v_bitop3_b32 v33, v182, v32, v172 bitop3:0x1e
	v_mov_b32_e32 v40, v109
	v_or_b32_e32 v44, s87, v178
	v_lshlrev_b32_e32 v45, 4, v33
	v_bitop3_b32 v32, v188, v32, v172 bitop3:0x1e
	v_pk_mul_f32 v[30:31], v[30:31], v[40:41] op_sel_hi:[1,0]
	v_pk_mul_f32 v[28:29], v[28:29], v[40:41] op_sel_hi:[1,0]
	v_pk_mul_f32 v[26:27], v[26:27], v[40:41] op_sel_hi:[1,0]
	v_pk_mul_f32 v[24:25], v[24:25], v[40:41] op_sel_hi:[1,0]
	v_pk_mul_f32 v[22:23], v[22:23], v[40:41] op_sel_hi:[1,0]
	v_pk_mul_f32 v[20:21], v[20:21], v[40:41] op_sel_hi:[1,0]
	v_pk_mul_f32 v[18:19], v[18:19], v[40:41] op_sel_hi:[1,0]
	v_pk_mul_f32 v[16:17], v[16:17], v[40:41] op_sel_hi:[1,0]
	v_pk_mul_f32 v[14:15], v[14:15], v[40:41] op_sel_hi:[1,0]
	v_pk_mul_f32 v[12:13], v[12:13], v[40:41] op_sel_hi:[1,0]
	v_pk_mul_f32 v[10:11], v[10:11], v[40:41] op_sel_hi:[1,0]
	v_pk_mul_f32 v[8:9], v[8:9], v[40:41] op_sel_hi:[1,0]
	v_pk_mul_f32 v[6:7], v[6:7], v[40:41] op_sel_hi:[1,0]
	v_pk_mul_f32 v[4:5], v[4:5], v[40:41] op_sel_hi:[1,0]
	v_pk_mul_f32 v[2:3], v[2:3], v[40:41] op_sel_hi:[1,0]
	v_add_u32_e32 v41, v45, v184
	v_lshlrev_b32_e32 v46, 4, v32
	v_add_u32_e32 v43, v176, v44
	v_add_u32_e32 v48, v180, v44
	v_add_u32_e32 v42, v46, v186
	v_add_u32_e32 v47, v164, v43
	v_add_u32_e32 v49, v165, v48
	ds_read_b64_tr_b16 v[36:37], v41
	ds_read_b64_tr_b16 v[38:39], v42
	ds_read_b64_tr_b16 v[32:33], v47
	ds_read_b64_tr_b16 v[34:35], v49
	s_waitcnt lgkmcnt(0)
	v_pk_mul_f32 v[0:1], v[0:1], v[40:41] op_sel_hi:[1,0]
	v_mfma_f32_32x32x16_bf16 v[16:31], v[36:39], v[32:35], v[16:31]
	v_add_u32_e32 v47, v162, v43
	v_add_u32_e32 v48, v163, v48
	ds_read_b64_tr_b16 v[32:33], v47
	ds_read_b64_tr_b16 v[34:35], v48
	ds_read_b64_tr_b16 v[40:41], v47
	ds_read_b64_tr_b16 v[42:43], v48
	s_waitcnt lgkmcnt(0)
	v_add_u32_e32 v47, v183, v44
	v_add_u32_e32 v42, v181, v44
	v_add_u32_e32 v40, v185, v45
	v_add_u32_e32 v41, v46, v187
	v_mfma_f32_32x32x16_bf16 v[0:15], v[36:39], v[32:35], v[0:15]
	v_add_u32_e32 v43, v42, v164
	v_add_u32_e32 v48, v165, v47
	ds_read_b64_tr_b16 v[36:37], v40
	ds_read_b64_tr_b16 v[38:39], v41
	ds_read_b64_tr_b16 v[32:33], v43
	ds_read_b64_tr_b16 v[34:35], v48
	s_waitcnt lgkmcnt(0)
	v_add_u32_e32 v48, v162, v42
	v_add_u32_e32 v47, v163, v47
	s_and_b64 vcc, exec, s[4:5]
	v_mfma_f32_32x32x16_bf16 v[16:31], v[36:39], v[32:35], v[16:31]
	ds_read_b64_tr_b16 v[32:33], v48
	ds_read_b64_tr_b16 v[34:35], v47
	ds_read_b64_tr_b16 v[40:41], v48
	ds_read_b64_tr_b16 v[42:43], v47
	s_waitcnt lgkmcnt(0)
	v_add_u32_e32 v47, v175, v44
	v_add_u32_e32 v42, v173, v44
	v_add_u32_e32 v40, v177, v45
	v_add_u32_e32 v41, v46, v179
	v_add_u32_e32 v43, v42, v164
	v_add_u32_e32 v48, v165, v47
	v_mfma_f32_32x32x16_bf16 v[0:15], v[36:39], v[32:35], v[0:15]
	ds_read_b64_tr_b16 v[36:37], v40
	ds_read_b64_tr_b16 v[38:39], v41
	ds_read_b64_tr_b16 v[32:33], v43
	ds_read_b64_tr_b16 v[34:35], v48
	s_waitcnt lgkmcnt(0)
	v_add_u32_e32 v48, v162, v42
	v_add_u32_e32 v47, v163, v47
	v_mfma_f32_32x32x16_bf16 v[16:31], v[36:39], v[32:35], v[16:31]
	ds_read_b64_tr_b16 v[32:33], v48
	ds_read_b64_tr_b16 v[34:35], v47
	ds_read_b64_tr_b16 v[40:41], v48
	ds_read_b64_tr_b16 v[42:43], v47
	s_waitcnt lgkmcnt(0)
	v_add_u32_e32 v47, v169, v44
	v_add_u32_e32 v42, v168, v44
	v_add_u32_e32 v40, v170, v45
	v_add_u32_e32 v41, v46, v171
	v_add_u32_e32 v43, v42, v164
	v_add_u32_e32 v48, v165, v47
	v_mfma_f32_32x32x16_bf16 v[0:15], v[36:39], v[32:35], v[0:15]
	ds_read_b64_tr_b16 v[36:37], v40
	ds_read_b64_tr_b16 v[38:39], v41
	ds_read_b64_tr_b16 v[32:33], v43
	ds_read_b64_tr_b16 v[34:35], v48
	s_waitcnt lgkmcnt(0)
	v_add_u32_e32 v48, v162, v42
	v_add_u32_e32 v47, v163, v47
	v_mfma_f32_32x32x16_bf16 v[16:31], v[36:39], v[32:35], v[16:31]
	ds_read_b64_tr_b16 v[32:33], v48
	ds_read_b64_tr_b16 v[34:35], v47
	ds_read_b64_tr_b16 v[40:41], v48
	ds_read_b64_tr_b16 v[42:43], v47
	s_waitcnt lgkmcnt(0)
	v_add_u32_e32 v47, v99, v44
	v_add_u32_e32 v42, v98, v44
	v_add_u32_e32 v40, v166, v45
	v_add_u32_e32 v41, v46, v167
	v_add_u32_e32 v43, v42, v164
	v_add_u32_e32 v48, v165, v47
	v_mfma_f32_32x32x16_bf16 v[0:15], v[36:39], v[32:35], v[0:15]
	ds_read_b64_tr_b16 v[36:37], v40
	ds_read_b64_tr_b16 v[38:39], v41
	ds_read_b64_tr_b16 v[32:33], v43
	ds_read_b64_tr_b16 v[34:35], v48
	s_waitcnt lgkmcnt(0)
	v_add_u32_e32 v48, v162, v42
	v_add_u32_e32 v47, v163, v47
	v_mfma_f32_32x32x16_bf16 v[16:31], v[36:39], v[32:35], v[16:31]
	ds_read_b64_tr_b16 v[32:33], v48
	ds_read_b64_tr_b16 v[34:35], v47
	ds_read_b64_tr_b16 v[40:41], v48
	ds_read_b64_tr_b16 v[42:43], v47
	s_waitcnt lgkmcnt(0)
	v_add_u32_e32 v47, v89, v44
	v_add_u32_e32 v42, v88, v44
	v_add_u32_e32 v40, v96, v45
	v_add_u32_e32 v41, v46, v97
	v_add_u32_e32 v43, v42, v164
	v_add_u32_e32 v48, v165, v47
	v_mfma_f32_32x32x16_bf16 v[0:15], v[36:39], v[32:35], v[0:15]
	ds_read_b64_tr_b16 v[36:37], v40
	ds_read_b64_tr_b16 v[38:39], v41
	ds_read_b64_tr_b16 v[32:33], v43
	ds_read_b64_tr_b16 v[34:35], v48
	s_waitcnt lgkmcnt(0)
	v_add_u32_e32 v48, v162, v42
	v_add_u32_e32 v47, v163, v47
	v_mfma_f32_32x32x16_bf16 v[16:31], v[36:39], v[32:35], v[16:31]
	ds_read_b64_tr_b16 v[32:33], v48
	ds_read_b64_tr_b16 v[34:35], v47
	ds_read_b64_tr_b16 v[40:41], v48
	ds_read_b64_tr_b16 v[42:43], v47
	s_waitcnt lgkmcnt(0)
	v_add_u32_e32 v47, v85, v44
	v_add_u32_e32 v42, v84, v44
	v_add_u32_e32 v40, v86, v45
	v_add_u32_e32 v41, v46, v87
	v_add_u32_e32 v43, v42, v164
	v_add_u32_e32 v48, v165, v47
	v_mfma_f32_32x32x16_bf16 v[0:15], v[36:39], v[32:35], v[0:15]
	ds_read_b64_tr_b16 v[36:37], v40
	ds_read_b64_tr_b16 v[38:39], v41
	ds_read_b64_tr_b16 v[32:33], v43
	ds_read_b64_tr_b16 v[34:35], v48
	s_waitcnt lgkmcnt(0)
	v_add_u32_e32 v48, v162, v42
	v_add_u32_e32 v47, v163, v47
	v_mfma_f32_32x32x16_bf16 v[16:31], v[36:39], v[32:35], v[16:31]
	ds_read_b64_tr_b16 v[32:33], v48
	ds_read_b64_tr_b16 v[34:35], v47
	ds_read_b64_tr_b16 v[40:41], v48
	ds_read_b64_tr_b16 v[42:43], v47
	s_waitcnt lgkmcnt(0)
	s_nop 0
	v_add_u32_e32 v42, v80, v44
	v_add_u32_e32 v44, v81, v44
	v_add_u32_e32 v40, v82, v45
	v_add_u32_e32 v41, v46, v83
	v_add_u32_e32 v43, v42, v164
	v_mfma_f32_32x32x16_bf16 v[0:15], v[36:39], v[32:35], v[0:15]
	v_add_u32_e32 v45, v165, v44
	ds_read_b64_tr_b16 v[36:37], v40
	ds_read_b64_tr_b16 v[38:39], v41
	ds_read_b64_tr_b16 v[32:33], v43
	ds_read_b64_tr_b16 v[34:35], v45
	s_waitcnt lgkmcnt(0)
	v_add_u32_e32 v45, v162, v42
	v_add_u32_e32 v44, v163, v44
	v_mfma_f32_32x32x16_bf16 v[16:31], v[36:39], v[32:35], v[16:31]
	ds_read_b64_tr_b16 v[32:33], v45
	ds_read_b64_tr_b16 v[34:35], v44
	ds_read_b64_tr_b16 v[40:41], v45
	ds_read_b64_tr_b16 v[42:43], v44
	s_waitcnt lgkmcnt(0)
	s_nop 0
	v_mfma_f32_32x32x16_bf16 v[0:15], v[36:39], v[32:35], v[0:15]
	s_cbranch_vccnz .LBB0_779
	v_lshlrev_b32_e32 v34, 8, v120
	s_movk_i32 s0, 0xe000
	v_and_or_b32 v34, v34, s0, v64
	v_and_b32_e32 v32, 0x7f, v132
	v_bfe_u32 v33, v132, 3, 4
	v_add_u32_e32 v34, 0, v34
	v_mov_b32_e32 v35, 0
	s_mov_b32 s1, 1

.Lp3_tail_next:
	s_add_i32 s99, s99, 1
	s_cmp_lt_u32 s99, 2
	s_cbranch_scc1 .Lp3_tail_step
	s_waitcnt lgkmcnt(0)
	s_barrier
	s_add_i32 s0, s63, 1
	s_cmp_eq_u32 s63, s75
	s_cbranch_scc1 .LBB0_781
	s_mov_b32 s63, s0
	s_branch .LBB0_757
